# scan: younger producer wave of each SIMD at priority 3 instead of 1 (immediate-only change)
# speedup vs baseline: 1.0077x; 1.0025x over previous
; __device__ __forceinline__ void lds_barrier() { asm volatile("s_waitcnt lgkmcnt(0)" ::: "memory"); __builtin_amdgcn_s_barrier(); asm volatile("" ::: "memory"); }
; __device__ __forceinline__ void phase_scan2(const Params& p, int l, LAS unsigned char* lds) {
;     ...
;         if (wid >= 3) { pload(pw); pbuild(pw, lds + pw * SC_SLOT, scr, SC_NP + pw); }
;         lds_barrier();
;         for (int rd = 0; rd < NRD; ++rd) {
;             if (wid == 0) {
; #pragma unroll 1
;                 for (int q = 0; q < SC_NP; ++q) { const int c = rd * SC_NP + q; if (c < NCH) consume(c, lds + ((rd & 1) * SC_NP + q) * SC_SLOT); }
;             } else if (wid >= 3) {
;                 const int cb = (rd + 1) * SC_NP + pw, cn = cb + SC_NP;
;                 if (cb < NCH) pbuild(cb, lds + (((rd + 1) & 1) * SC_NP + pw) * SC_SLOT, scr, cn < NCH ? cn : -1);
.Lsc_producer:
	s_sub_u32 s55, s25, 1
	s_cmp_gt_u32 s25, 4
	s_cselect_b32 s0, 1, 0
	s_sub_u32 s55, s55, s0
	s_cmp_gt_u32 s25, 4
	s_cbranch_scc0 .Lsc_p_noprio
	s_setprio 3
